# residual epilogue stores sc1+nt (write-through, streaming) on top of nt residual loads
# speedup vs baseline: 1.0081x; 1.0081x over previous
;     __device__ __forceinline__ void operator()(const f32x4 (&acc)[2][2][4][2], const Unit& u, int wr, int wc, int fr, int fq) const {
;         const float* src; float* dst; int b;
;         if (u.pm < 128) { src = src_lat + (size_t)u.pm * BM * 1024; dst = dst_lat + (size_t)u.pm * BM * 1024; b = u.pm >> 5; }
;         else { src = src_ctx + (size_t)(u.pm - 128) * BM * 1024; dst = dst_ctx + (size_t)(u.pm - 128) * BM * 1024; b = 4; }
;         const float* g = gate + b * 6144;
;         const int col0 = u.pn * BM + wc * 32 + 4 * fq;
; #pragma unroll
;         for (int bj = 0; bj < 2; ++bj)
; #pragma unroll
;             for (int n = 0; n < 2; ++n) { const f32x4 gv = *(const f32x4*)(g + col0 + bj * HALF + n * 16);
; #pragma unroll
;                 for (int ai = 0; ai < 2; ++ai)
; #pragma unroll
;                     for (int m = 0; m < 4; ++m) { const size_t off = (size_t)(ai * HALF + wr * 64 + m * 16 + fr) * 1024 + col0 + bj * HALF + n * 16;
;                         const f32x4 s = *(const f32x4*)(src + off); *(f32x4*)(dst + off) = s + gv * acc[ai][bj][m][n]; } }
.LBB0_549:
	s_lshl_b64 s[14:15], s[20:21], 2
	s_add_u32 s14, s35, s14
	s_addc_u32 s15, s36, s15
	s_add_u32 s20, s18, 0x80000
	s_addc_u32 s21, s19, 0
	s_add_u32 s22, s16, 0x80000
	s_addc_u32 s23, s17, 0
	v_mbcnt_lo_u32_b32 v186, -1, 0
	v_mbcnt_hi_u32_b32 v186, -1, v186
	v_lshrrev_b32_e32 v187, 10, v142
	v_and_b32_e32 v187, 64, v187
	v_and_b32_e32 v188, 0x60, v169
	v_mul_u32_u24_e32 v189, 0xc0, v187
	v_mul_u32_u24_e32 v192, 0x60, v188
	v_add_u32_e32 v189, v189, v192
	v_add_u32_e32 v189, 0x20000, v189
	v_and_b32_e32 v192, 15, v186
	v_lshrrev_b32_e32 v193, 4, v186
	v_mul_u32_u24_e32 v192, 0x90, v192
	v_lshl_add_u32 v192, v193, 4, v192
	v_add_u32_e32 v38, v189, v192
	v_lshrrev_b32_e32 v190, 3, v186
	v_and_b32_e32 v191, 7, v186
	v_mul_u32_u24_e32 v192, 0x90, v190
	v_lshl_add_u32 v192, v191, 4, v192
	v_add_u32_e32 v250, v189, v192
	v_add_u32_e32 v193, v187, v190
	v_lshlrev_b32_e32 v193, 12, v193
	v_lshl_or_b32 v193, v188, 2, v193
	v_lshl_or_b32 v193, v191, 4, v193
	v_lshl_or_b32 v166, s40, 10, v193
	v_and_b32_e32 v251, 0xfff, v166
	v_add_u32_e32 v167, 0x8000, v166
	v_add_u32_e32 v180, 0x10000, v166
	v_add_u32_e32 v181, 0x18000, v166
	v_add_u32_e32 v202, 0x20000, v166
	v_add_u32_e32 v203, 0x28000, v166
	v_add_u32_e32 v212, 0x30000, v166
	v_add_u32_e32 v213, 0x38000, v166
	global_load_dwordx4 v[138:141], v251, s[14:15]
	global_load_dwordx4 v[162:165], v251, s[14:15] offset:512
	global_load_dwordx4 v[172:175], v166, s[18:19] nt
	global_load_dwordx4 v[176:179], v166, s[18:19] offset:512 nt
	global_load_dwordx4 v[186:189], v167, s[18:19] nt
	global_load_dwordx4 v[190:193], v167, s[18:19] offset:512 nt
	global_load_dwordx4 v[194:197], v180, s[18:19] nt
	global_load_dwordx4 v[198:201], v180, s[18:19] offset:512 nt
	global_load_dwordx4 v[208:211], v181, s[18:19] nt
	global_load_dwordx4 v[218:221], v181, s[18:19] offset:512 nt
	global_load_dwordx4 v[226:229], v202, s[18:19] nt
	global_load_dwordx4 v[230:233], v202, s[18:19] offset:512 nt
	global_load_dwordx4 v[234:237], v203, s[18:19] nt
	global_load_dwordx4 v[238:241], v203, s[18:19] offset:512 nt
	global_load_dwordx4 v[242:245], v212, s[18:19] nt
	global_load_dwordx4 v[246:249], v212, s[18:19] offset:512 nt
	ds_write_b128 v38, v[134:137]
	ds_write_b128 v38, v[106:109] offset:64
	ds_read_b128 v[134:137], v250
	ds_read_b128 v[106:109], v250 offset:1152
	ds_write_b128 v38, v[82:85]
	ds_write_b128 v38, v[54:57] offset:64
	ds_read_b128 v[82:85], v250
	ds_read_b128 v[54:57], v250 offset:1152
	ds_write_b128 v38, v[130:133]
	ds_write_b128 v38, v[102:105] offset:64
	ds_read_b128 v[130:133], v250
	ds_read_b128 v[102:105], v250 offset:1152
	ds_write_b128 v38, v[74:77]
	ds_write_b128 v38, v[46:49] offset:64
	ds_read_b128 v[74:77], v250
	ds_read_b128 v[46:49], v250 offset:1152
	ds_write_b128 v38, v[126:129]
	ds_write_b128 v38, v[98:101] offset:64
	ds_read_b128 v[126:129], v250
	ds_read_b128 v[98:101], v250 offset:1152
	ds_write_b128 v38, v[66:69]
	ds_write_b128 v38, v[30:33] offset:64
	ds_read_b128 v[66:69], v250
	ds_read_b128 v[30:33], v250 offset:1152
	ds_write_b128 v38, v[122:125]
	ds_write_b128 v38, v[90:93] offset:64
	ds_read_b128 v[122:125], v250
	ds_read_b128 v[90:93], v250 offset:1152
	ds_write_b128 v38, v[58:61]
	ds_write_b128 v38, v[22:25] offset:64
	ds_read_b128 v[58:61], v250
	ds_read_b128 v[22:25], v250 offset:1152
	ds_write_b128 v38, v[118:121]
	ds_write_b128 v38, v[86:89] offset:64
	ds_read_b128 v[118:121], v250
	ds_read_b128 v[86:89], v250 offset:1152
	ds_write_b128 v38, v[50:53]
	ds_write_b128 v38, v[14:17] offset:64
	ds_read_b128 v[50:53], v250
	ds_read_b128 v[14:17], v250 offset:1152
	ds_write_b128 v38, v[114:117]
	ds_write_b128 v38, v[78:81] offset:64
	ds_read_b128 v[114:117], v250
	ds_read_b128 v[78:81], v250 offset:1152
	ds_write_b128 v38, v[42:45]
	ds_write_b128 v38, v[10:13] offset:64
	ds_read_b128 v[42:45], v250
	ds_read_b128 v[10:13], v250 offset:1152
	ds_write_b128 v38, v[110:113]
	ds_write_b128 v38, v[70:73] offset:64
	ds_read_b128 v[110:113], v250
	ds_read_b128 v[70:73], v250 offset:1152
	ds_write_b128 v38, v[26:29]
	ds_write_b128 v38, v[6:9] offset:64
	ds_read_b128 v[26:29], v250
	ds_read_b128 v[6:9], v250 offset:1152
	ds_write_b128 v38, v[94:97]
	ds_write_b128 v38, v[62:65] offset:64
	ds_read_b128 v[94:97], v250
	ds_read_b128 v[62:65], v250 offset:1152
	ds_write_b128 v38, v[18:21]
	ds_write_b128 v38, v[2:5] offset:64
	ds_read_b128 v[18:21], v250
	ds_read_b128 v[2:5], v250 offset:1152
	s_waitcnt lgkmcnt(0)
	s_waitcnt vmcnt(13)
	v_pk_fma_f32 v[134:135], v[134:135], v[138:139], v[172:173]
	v_pk_fma_f32 v[136:137], v[136:137], v[140:141], v[174:175]
	global_store_dwordx4 v166, v[134:137], s[16:17] sc1 nt
	global_load_dwordx4 v[172:175], v213, s[18:19] nt
	s_waitcnt vmcnt(14)
	v_pk_fma_f32 v[82:83], v[82:83], v[162:163], v[176:177]
	v_pk_fma_f32 v[84:85], v[84:85], v[164:165], v[178:179]
	global_store_dwordx4 v166, v[82:85], s[16:17] offset:512 sc1 nt
	global_load_dwordx4 v[176:179], v213, s[18:19] offset:512 nt
	s_waitcnt vmcnt(15)
	v_pk_fma_f32 v[106:107], v[106:107], v[138:139], v[186:187]
	v_pk_fma_f32 v[108:109], v[108:109], v[140:141], v[188:189]
	global_store_dwordx4 v167, v[106:109], s[16:17] sc1 nt
	global_load_dwordx4 v[186:189], v166, s[20:21] nt
	s_waitcnt vmcnt(16)
	v_pk_fma_f32 v[54:55], v[54:55], v[162:163], v[190:191]
	v_pk_fma_f32 v[56:57], v[56:57], v[164:165], v[192:193]
	global_store_dwordx4 v167, v[54:57], s[16:17] offset:512 sc1 nt
	global_load_dwordx4 v[190:193], v166, s[20:21] offset:512 nt
	s_waitcnt vmcnt(17)
	v_pk_fma_f32 v[130:131], v[130:131], v[138:139], v[194:195]
	v_pk_fma_f32 v[132:133], v[132:133], v[140:141], v[196:197]
	global_store_dwordx4 v180, v[130:133], s[16:17] sc1 nt
	global_load_dwordx4 v[194:197], v167, s[20:21] nt
	s_waitcnt vmcnt(18)
; #define PG8_BAR __builtin_amdgcn_s_barrier()
;     __device__ __forceinline__ void operator()(const f32x4 (&acc)[2][2][4][2], const Unit& u, int wr, int wc, int fr, int fq) const {
;     ...
;             for (int n = 0; n < 2; ++n) { const f32x4 gv = *(const f32x4*)(g + col0 + bj * HALF + n * 16);
; #pragma unroll
;                 for (int ai = 0; ai < 2; ++ai)
; #pragma unroll
;                     for (int m = 0; m < 4; ++m) { const size_t off = (size_t)(ai * HALF + wr * 64 + m * 16 + fr) * 1024 + col0 + bj * HALF + n * 16;
;                         const f32x4 s = *(const f32x4*)(src + off); *(f32x4*)(dst + off) = s + gv * acc[ai][bj][m][n]; } }
; template <class Epi, class Sched, bool ALIGN_EPI = false, bool SP2 = false>
; __device__ __forceinline__ void gemm_phase(PG8_LAS unsigned char* lds, const Gemm g, const Sched& S, const Epi& E) {
;     ...
;         if constexpr (ALIGN_EPI) { if (wr == 0) PG8_BAR; }
;         if constexpr (!Epi::AFTER_DRAIN) { E(acc, cur, wr, wc, fr, fq); S.done(cur); }
;         if (!has_next) break;
; #pragma unroll
;         for (int a = 0; a < 2; ++a)
; #pragma unroll
;             for (int b = 0; b < 2; ++b)
; #pragma unroll
;                 for (int m = 0; m < 4; ++m)
; #pragma unroll
;                     for (int n = 0; n < 2; ++n) acc[a][b][m][n] = (f32x4){0.f, 0.f, 0.f, 0.f};
;         cur = nxt; cA = nA; cB = nB; ++ui;
;         if constexpr (ALIGN_EPI) { if (wr == 1) PG8_BAR; }
	v_pk_fma_f32 v[74:75], v[74:75], v[162:163], v[198:199]
	v_pk_fma_f32 v[76:77], v[76:77], v[164:165], v[200:201]
	global_store_dwordx4 v180, v[74:77], s[16:17] offset:512 sc1 nt
	global_load_dwordx4 v[198:201], v167, s[20:21] offset:512 nt
	s_waitcnt vmcnt(19)
	v_pk_fma_f32 v[102:103], v[102:103], v[138:139], v[208:209]
	v_pk_fma_f32 v[104:105], v[104:105], v[140:141], v[210:211]
	global_store_dwordx4 v181, v[102:105], s[16:17] sc1 nt
	global_load_dwordx4 v[208:211], v180, s[20:21] nt
	s_waitcnt vmcnt(20)
	v_pk_fma_f32 v[46:47], v[46:47], v[162:163], v[218:219]
	v_pk_fma_f32 v[48:49], v[48:49], v[164:165], v[220:221]
	global_store_dwordx4 v181, v[46:49], s[16:17] offset:512 sc1 nt
	global_load_dwordx4 v[218:221], v180, s[20:21] offset:512 nt
	s_waitcnt vmcnt(21)
	v_pk_fma_f32 v[126:127], v[126:127], v[138:139], v[226:227]
	v_pk_fma_f32 v[128:129], v[128:129], v[140:141], v[228:229]
	global_store_dwordx4 v202, v[126:129], s[16:17] sc1 nt
	global_load_dwordx4 v[226:229], v181, s[20:21] nt
	s_waitcnt vmcnt(22)
	v_pk_fma_f32 v[66:67], v[66:67], v[162:163], v[230:231]
	v_pk_fma_f32 v[68:69], v[68:69], v[164:165], v[232:233]
	global_store_dwordx4 v202, v[66:69], s[16:17] offset:512 sc1 nt
	global_load_dwordx4 v[230:233], v181, s[20:21] offset:512 nt
	s_waitcnt vmcnt(23)
	v_pk_fma_f32 v[98:99], v[98:99], v[138:139], v[234:235]
	v_pk_fma_f32 v[100:101], v[100:101], v[140:141], v[236:237]
	global_store_dwordx4 v203, v[98:101], s[16:17] sc1 nt
	global_load_dwordx4 v[234:237], v202, s[20:21] nt
	s_waitcnt vmcnt(24)
	v_pk_fma_f32 v[30:31], v[30:31], v[162:163], v[238:239]
	v_pk_fma_f32 v[32:33], v[32:33], v[164:165], v[240:241]
	global_store_dwordx4 v203, v[30:33], s[16:17] offset:512 sc1 nt
	global_load_dwordx4 v[238:241], v202, s[20:21] offset:512 nt
	s_waitcnt vmcnt(25)
	v_pk_fma_f32 v[122:123], v[122:123], v[138:139], v[242:243]
	v_pk_fma_f32 v[124:125], v[124:125], v[140:141], v[244:245]
	global_store_dwordx4 v212, v[122:125], s[16:17] sc1 nt
	global_load_dwordx4 v[242:245], v203, s[20:21] nt
	s_waitcnt vmcnt(26)
	v_pk_fma_f32 v[58:59], v[58:59], v[162:163], v[246:247]
	v_pk_fma_f32 v[60:61], v[60:61], v[164:165], v[248:249]
	global_store_dwordx4 v212, v[58:61], s[16:17] offset:512 sc1 nt
	global_load_dwordx4 v[246:249], v203, s[20:21] offset:512 nt
	s_waitcnt vmcnt(26)
	v_pk_fma_f32 v[90:91], v[90:91], v[138:139], v[172:173]
	v_pk_fma_f32 v[92:93], v[92:93], v[140:141], v[174:175]
	global_store_dwordx4 v213, v[90:93], s[16:17] sc1 nt
	global_load_dwordx4 v[172:175], v212, s[20:21] nt
	s_waitcnt vmcnt(26)
	v_pk_fma_f32 v[22:23], v[22:23], v[162:163], v[176:177]
	v_pk_fma_f32 v[24:25], v[24:25], v[164:165], v[178:179]
	global_store_dwordx4 v213, v[22:25], s[16:17] offset:512 sc1 nt
	global_load_dwordx4 v[176:179], v212, s[20:21] offset:512 nt
	s_waitcnt vmcnt(26)
	v_pk_fma_f32 v[118:119], v[118:119], v[138:139], v[186:187]
	v_pk_fma_f32 v[120:121], v[120:121], v[140:141], v[188:189]
	global_store_dwordx4 v166, v[118:121], s[22:23] sc1 nt
	global_load_dwordx4 v[186:189], v213, s[20:21] nt
	s_waitcnt vmcnt(26)
	v_pk_fma_f32 v[50:51], v[50:51], v[162:163], v[190:191]
	v_pk_fma_f32 v[52:53], v[52:53], v[164:165], v[192:193]
	global_store_dwordx4 v166, v[50:53], s[22:23] offset:512 sc1 nt
	global_load_dwordx4 v[190:193], v213, s[20:21] offset:512 nt
	s_waitcnt vmcnt(26)
	v_pk_fma_f32 v[86:87], v[86:87], v[138:139], v[194:195]
	v_pk_fma_f32 v[88:89], v[88:89], v[140:141], v[196:197]
	global_store_dwordx4 v167, v[86:89], s[22:23] sc1 nt
	s_waitcnt vmcnt(25)
	v_pk_fma_f32 v[14:15], v[14:15], v[162:163], v[198:199]
	v_pk_fma_f32 v[16:17], v[16:17], v[164:165], v[200:201]
	global_store_dwordx4 v167, v[14:17], s[22:23] offset:512 sc1 nt
	s_waitcnt vmcnt(24)
	v_pk_fma_f32 v[114:115], v[114:115], v[138:139], v[208:209]
	v_pk_fma_f32 v[116:117], v[116:117], v[140:141], v[210:211]
	global_store_dwordx4 v180, v[114:117], s[22:23] sc1 nt
	s_waitcnt vmcnt(23)
	v_pk_fma_f32 v[42:43], v[42:43], v[162:163], v[218:219]
	v_pk_fma_f32 v[44:45], v[44:45], v[164:165], v[220:221]
	global_store_dwordx4 v180, v[42:45], s[22:23] offset:512 sc1 nt
	s_waitcnt vmcnt(22)
	v_pk_fma_f32 v[78:79], v[78:79], v[138:139], v[226:227]
	v_pk_fma_f32 v[80:81], v[80:81], v[140:141], v[228:229]
	global_store_dwordx4 v181, v[78:81], s[22:23] sc1 nt
	s_waitcnt vmcnt(21)
	v_pk_fma_f32 v[10:11], v[10:11], v[162:163], v[230:231]
	v_pk_fma_f32 v[12:13], v[12:13], v[164:165], v[232:233]
	global_store_dwordx4 v181, v[10:13], s[22:23] offset:512 sc1 nt
	s_waitcnt vmcnt(20)
	v_pk_fma_f32 v[110:111], v[110:111], v[138:139], v[234:235]
	v_pk_fma_f32 v[112:113], v[112:113], v[140:141], v[236:237]
	global_store_dwordx4 v202, v[110:113], s[22:23] sc1 nt
	s_waitcnt vmcnt(19)
	v_pk_fma_f32 v[26:27], v[26:27], v[162:163], v[238:239]
	v_pk_fma_f32 v[28:29], v[28:29], v[164:165], v[240:241]
	global_store_dwordx4 v202, v[26:29], s[22:23] offset:512 sc1 nt
	s_waitcnt vmcnt(18)
	v_pk_fma_f32 v[70:71], v[70:71], v[138:139], v[242:243]
	v_pk_fma_f32 v[72:73], v[72:73], v[140:141], v[244:245]
	global_store_dwordx4 v203, v[70:73], s[22:23] sc1 nt
	s_waitcnt vmcnt(17)
	v_pk_fma_f32 v[6:7], v[6:7], v[162:163], v[246:247]
	v_pk_fma_f32 v[8:9], v[8:9], v[164:165], v[248:249]
	global_store_dwordx4 v203, v[6:9], s[22:23] offset:512 sc1 nt
	s_waitcnt vmcnt(16)
	v_pk_fma_f32 v[94:95], v[94:95], v[138:139], v[172:173]
	v_pk_fma_f32 v[96:97], v[96:97], v[140:141], v[174:175]
	global_store_dwordx4 v212, v[94:97], s[22:23] sc1 nt
	s_waitcnt vmcnt(15)
	v_pk_fma_f32 v[18:19], v[18:19], v[162:163], v[176:177]
	v_pk_fma_f32 v[20:21], v[20:21], v[164:165], v[178:179]
	global_store_dwordx4 v212, v[18:21], s[22:23] offset:512 sc1 nt
	s_waitcnt vmcnt(14)
	v_pk_fma_f32 v[62:63], v[62:63], v[138:139], v[186:187]
	v_pk_fma_f32 v[64:65], v[64:65], v[140:141], v[188:189]
	global_store_dwordx4 v213, v[62:65], s[22:23] sc1 nt
	s_waitcnt vmcnt(13)
	v_pk_fma_f32 v[2:3], v[2:3], v[162:163], v[190:191]
	v_pk_fma_f32 v[4:5], v[4:5], v[164:165], v[192:193]
	global_store_dwordx4 v213, v[2:5], s[22:23] offset:512 sc1 nt
	s_mov_b64 s[14:15], -1
	s_andn2_b64 vcc, exec, s[4:5]
	s_cbranch_vccnz .LBB0_534
	s_andn2_b64 vcc, exec, s[0:1]
	s_cbranch_vccnz .LBB0_533
	s_barrier
	s_branch .LBB0_533

;     __device__ __forceinline__ void operator()(const f32x4 (&acc)[2][2][4][2], const Unit& u, int wr, int wc, int fr, int fq) const {
;         const float* src; float* dst; int b;
;         if (u.pm < 128) { src = src_lat + (size_t)u.pm * BM * 1024; dst = dst_lat + (size_t)u.pm * BM * 1024; b = u.pm >> 5; }
;         else { src = src_ctx + (size_t)(u.pm - 128) * BM * 1024; dst = dst_ctx + (size_t)(u.pm - 128) * BM * 1024; b = 4; }
;         const float* g = gate + b * 6144;
;         const int col0 = u.pn * BM + wc * 32 + 4 * fq;
; #pragma unroll
;         for (int bj = 0; bj < 2; ++bj)
; #pragma unroll
;             for (int n = 0; n < 2; ++n) { const f32x4 gv = *(const f32x4*)(g + col0 + bj * HALF + n * 16);
; #pragma unroll
;                 for (int ai = 0; ai < 2; ++ai)
; #pragma unroll
;                     for (int m = 0; m < 4; ++m) { const size_t off = (size_t)(ai * HALF + wr * 64 + m * 16 + fr) * 1024 + col0 + bj * HALF + n * 16;
;                         const f32x4 s = *(const f32x4*)(src + off); *(f32x4*)(dst + off) = s + gv * acc[ai][bj][m][n]; } }
.LBB0_995:
	s_lshl_b64 s[10:11], s[16:17], 2
	s_add_u32 s10, s31, s10
	s_addc_u32 s11, s34, s11
	s_add_u32 s16, s14, 0x80000
	s_addc_u32 s17, s15, 0
	s_add_u32 s18, s12, 0x80000
	s_addc_u32 s19, s13, 0
	v_mbcnt_lo_u32_b32 v186, -1, 0
	v_mbcnt_hi_u32_b32 v186, -1, v186
	v_lshrrev_b32_e32 v187, 10, v142
	v_and_b32_e32 v187, 64, v187
	v_and_b32_e32 v188, 0x60, v169
	v_mul_u32_u24_e32 v189, 0xc0, v187
	v_mul_u32_u24_e32 v192, 0x60, v188
	v_add_u32_e32 v189, v189, v192
	v_add_u32_e32 v189, 0x20000, v189
	v_and_b32_e32 v192, 15, v186
	v_lshrrev_b32_e32 v193, 4, v186
	v_mul_u32_u24_e32 v192, 0x90, v192
	v_lshl_add_u32 v192, v193, 4, v192
	v_add_u32_e32 v38, v189, v192
	v_lshrrev_b32_e32 v190, 3, v186
	v_and_b32_e32 v191, 7, v186
	v_mul_u32_u24_e32 v192, 0x90, v190
	v_lshl_add_u32 v192, v191, 4, v192
	v_add_u32_e32 v250, v189, v192
	v_add_u32_e32 v193, v187, v190
	v_lshlrev_b32_e32 v193, 12, v193
	v_lshl_or_b32 v193, v188, 2, v193
	v_lshl_or_b32 v193, v191, 4, v193
	v_lshl_or_b32 v166, s40, 10, v193
	v_and_b32_e32 v251, 0xfff, v166
	v_add_u32_e32 v167, 0x8000, v166
	v_add_u32_e32 v180, 0x10000, v166
	v_add_u32_e32 v181, 0x18000, v166
	v_add_u32_e32 v202, 0x20000, v166
	v_add_u32_e32 v203, 0x28000, v166
	v_add_u32_e32 v212, 0x30000, v166
	v_add_u32_e32 v213, 0x38000, v166
	global_load_dwordx4 v[138:141], v251, s[10:11]
	global_load_dwordx4 v[162:165], v251, s[10:11] offset:512
	global_load_dwordx4 v[172:175], v166, s[14:15] nt
	global_load_dwordx4 v[176:179], v166, s[14:15] offset:512 nt
	global_load_dwordx4 v[186:189], v167, s[14:15] nt
	global_load_dwordx4 v[190:193], v167, s[14:15] offset:512 nt
	global_load_dwordx4 v[194:197], v180, s[14:15] nt
	global_load_dwordx4 v[198:201], v180, s[14:15] offset:512 nt
	global_load_dwordx4 v[208:211], v181, s[14:15] nt
	global_load_dwordx4 v[218:221], v181, s[14:15] offset:512 nt
	global_load_dwordx4 v[226:229], v202, s[14:15] nt
	global_load_dwordx4 v[230:233], v202, s[14:15] offset:512 nt
	global_load_dwordx4 v[234:237], v203, s[14:15] nt
	global_load_dwordx4 v[238:241], v203, s[14:15] offset:512 nt
	global_load_dwordx4 v[242:245], v212, s[14:15] nt
	global_load_dwordx4 v[246:249], v212, s[14:15] offset:512 nt
	ds_write_b128 v38, v[134:137]
	ds_write_b128 v38, v[106:109] offset:64
	ds_read_b128 v[134:137], v250
	ds_read_b128 v[106:109], v250 offset:1152
	ds_write_b128 v38, v[82:85]
	ds_write_b128 v38, v[54:57] offset:64
	ds_read_b128 v[82:85], v250
	ds_read_b128 v[54:57], v250 offset:1152
	ds_write_b128 v38, v[130:133]
	ds_write_b128 v38, v[102:105] offset:64
	ds_read_b128 v[130:133], v250
	ds_read_b128 v[102:105], v250 offset:1152
	ds_write_b128 v38, v[74:77]
	ds_write_b128 v38, v[46:49] offset:64
	ds_read_b128 v[74:77], v250
	ds_read_b128 v[46:49], v250 offset:1152
	ds_write_b128 v38, v[126:129]
	ds_write_b128 v38, v[98:101] offset:64
	ds_read_b128 v[126:129], v250
	ds_read_b128 v[98:101], v250 offset:1152
	ds_write_b128 v38, v[66:69]
	ds_write_b128 v38, v[30:33] offset:64
	ds_read_b128 v[66:69], v250
	ds_read_b128 v[30:33], v250 offset:1152
	ds_write_b128 v38, v[122:125]
	ds_write_b128 v38, v[90:93] offset:64
	ds_read_b128 v[122:125], v250
	ds_read_b128 v[90:93], v250 offset:1152
	ds_write_b128 v38, v[58:61]
	ds_write_b128 v38, v[22:25] offset:64
	ds_read_b128 v[58:61], v250
	ds_read_b128 v[22:25], v250 offset:1152
	ds_write_b128 v38, v[118:121]
	ds_write_b128 v38, v[86:89] offset:64
	ds_read_b128 v[118:121], v250
	ds_read_b128 v[86:89], v250 offset:1152
	ds_write_b128 v38, v[50:53]
	ds_write_b128 v38, v[14:17] offset:64
	ds_read_b128 v[50:53], v250
	ds_read_b128 v[14:17], v250 offset:1152
	ds_write_b128 v38, v[114:117]
	ds_write_b128 v38, v[78:81] offset:64
	ds_read_b128 v[114:117], v250
	ds_read_b128 v[78:81], v250 offset:1152
	ds_write_b128 v38, v[42:45]
	ds_write_b128 v38, v[10:13] offset:64
	ds_read_b128 v[42:45], v250
	ds_read_b128 v[10:13], v250 offset:1152
	ds_write_b128 v38, v[110:113]
	ds_write_b128 v38, v[70:73] offset:64
	ds_read_b128 v[110:113], v250
	ds_read_b128 v[70:73], v250 offset:1152
	ds_write_b128 v38, v[26:29]
	ds_write_b128 v38, v[6:9] offset:64
	ds_read_b128 v[26:29], v250
	ds_read_b128 v[6:9], v250 offset:1152
	ds_write_b128 v38, v[94:97]
	ds_write_b128 v38, v[62:65] offset:64
	ds_read_b128 v[94:97], v250
	ds_read_b128 v[62:65], v250 offset:1152
	ds_write_b128 v38, v[18:21]
	ds_write_b128 v38, v[2:5] offset:64
	ds_read_b128 v[18:21], v250
	ds_read_b128 v[2:5], v250 offset:1152
	s_waitcnt lgkmcnt(0)
	s_waitcnt vmcnt(13)
	v_pk_fma_f32 v[134:135], v[134:135], v[138:139], v[172:173]
	v_pk_fma_f32 v[136:137], v[136:137], v[140:141], v[174:175]
	global_store_dwordx4 v166, v[134:137], s[12:13] sc1 nt
	global_load_dwordx4 v[172:175], v213, s[14:15] nt
	s_waitcnt vmcnt(14)
	v_pk_fma_f32 v[82:83], v[82:83], v[162:163], v[176:177]
	v_pk_fma_f32 v[84:85], v[84:85], v[164:165], v[178:179]
	global_store_dwordx4 v166, v[82:85], s[12:13] offset:512 sc1 nt
	global_load_dwordx4 v[176:179], v213, s[14:15] offset:512 nt
	s_waitcnt vmcnt(15)
	v_pk_fma_f32 v[106:107], v[106:107], v[138:139], v[186:187]
	v_pk_fma_f32 v[108:109], v[108:109], v[140:141], v[188:189]
	global_store_dwordx4 v167, v[106:109], s[12:13] sc1 nt
	global_load_dwordx4 v[186:189], v166, s[16:17] nt
	s_waitcnt vmcnt(16)
	v_pk_fma_f32 v[54:55], v[54:55], v[162:163], v[190:191]
	v_pk_fma_f32 v[56:57], v[56:57], v[164:165], v[192:193]
	global_store_dwordx4 v167, v[54:57], s[12:13] offset:512 sc1 nt
	global_load_dwordx4 v[190:193], v166, s[16:17] offset:512 nt
	s_waitcnt vmcnt(17)
	v_pk_fma_f32 v[130:131], v[130:131], v[138:139], v[194:195]
	v_pk_fma_f32 v[132:133], v[132:133], v[140:141], v[196:197]
	global_store_dwordx4 v180, v[130:133], s[12:13] sc1 nt
	global_load_dwordx4 v[194:197], v167, s[16:17] nt
	s_waitcnt vmcnt(18)
; #define PG8_BAR __builtin_amdgcn_s_barrier()
;     __device__ __forceinline__ void operator()(const f32x4 (&acc)[2][2][4][2], const Unit& u, int wr, int wc, int fr, int fq) const {
;     ...
;             for (int n = 0; n < 2; ++n) { const f32x4 gv = *(const f32x4*)(g + col0 + bj * HALF + n * 16);
; #pragma unroll
;                 for (int ai = 0; ai < 2; ++ai)
; #pragma unroll
;                     for (int m = 0; m < 4; ++m) { const size_t off = (size_t)(ai * HALF + wr * 64 + m * 16 + fr) * 1024 + col0 + bj * HALF + n * 16;
;                         const f32x4 s = *(const f32x4*)(src + off); *(f32x4*)(dst + off) = s + gv * acc[ai][bj][m][n]; } }
; template <class Epi, class Sched, bool ALIGN_EPI = false, bool SP2 = false>
; __device__ __forceinline__ void gemm_phase(PG8_LAS unsigned char* lds, const Gemm g, const Sched& S, const Epi& E) {
;     ...
;         if constexpr (ALIGN_EPI) { if (wr == 0) PG8_BAR; }
;         if constexpr (!Epi::AFTER_DRAIN) { E(acc, cur, wr, wc, fr, fq); S.done(cur); }
;         if (!has_next) break;
; #pragma unroll
;         for (int a = 0; a < 2; ++a)
; #pragma unroll
;             for (int b = 0; b < 2; ++b)
; #pragma unroll
;                 for (int m = 0; m < 4; ++m)
; #pragma unroll
;                     for (int n = 0; n < 2; ++n) acc[a][b][m][n] = (f32x4){0.f, 0.f, 0.f, 0.f};
;         cur = nxt; cA = nA; cB = nB; ++ui;
;         if constexpr (ALIGN_EPI) { if (wr == 1) PG8_BAR; }
	v_pk_fma_f32 v[74:75], v[74:75], v[162:163], v[198:199]
	v_pk_fma_f32 v[76:77], v[76:77], v[164:165], v[200:201]
	global_store_dwordx4 v180, v[74:77], s[12:13] offset:512 sc1 nt
	global_load_dwordx4 v[198:201], v167, s[16:17] offset:512 nt
	s_waitcnt vmcnt(19)
	v_pk_fma_f32 v[102:103], v[102:103], v[138:139], v[208:209]
	v_pk_fma_f32 v[104:105], v[104:105], v[140:141], v[210:211]
	global_store_dwordx4 v181, v[102:105], s[12:13] sc1 nt
	global_load_dwordx4 v[208:211], v180, s[16:17] nt
	s_waitcnt vmcnt(20)
	v_pk_fma_f32 v[46:47], v[46:47], v[162:163], v[218:219]
	v_pk_fma_f32 v[48:49], v[48:49], v[164:165], v[220:221]
	global_store_dwordx4 v181, v[46:49], s[12:13] offset:512 sc1 nt
	global_load_dwordx4 v[218:221], v180, s[16:17] offset:512 nt
	s_waitcnt vmcnt(21)
	v_pk_fma_f32 v[126:127], v[126:127], v[138:139], v[226:227]
	v_pk_fma_f32 v[128:129], v[128:129], v[140:141], v[228:229]
	global_store_dwordx4 v202, v[126:129], s[12:13] sc1 nt
	global_load_dwordx4 v[226:229], v181, s[16:17] nt
	s_waitcnt vmcnt(22)
	v_pk_fma_f32 v[66:67], v[66:67], v[162:163], v[230:231]
	v_pk_fma_f32 v[68:69], v[68:69], v[164:165], v[232:233]
	global_store_dwordx4 v202, v[66:69], s[12:13] offset:512 sc1 nt
	global_load_dwordx4 v[230:233], v181, s[16:17] offset:512 nt
	s_waitcnt vmcnt(23)
	v_pk_fma_f32 v[98:99], v[98:99], v[138:139], v[234:235]
	v_pk_fma_f32 v[100:101], v[100:101], v[140:141], v[236:237]
	global_store_dwordx4 v203, v[98:101], s[12:13] sc1 nt
	global_load_dwordx4 v[234:237], v202, s[16:17] nt
	s_waitcnt vmcnt(24)
	v_pk_fma_f32 v[30:31], v[30:31], v[162:163], v[238:239]
	v_pk_fma_f32 v[32:33], v[32:33], v[164:165], v[240:241]
	global_store_dwordx4 v203, v[30:33], s[12:13] offset:512 sc1 nt
	global_load_dwordx4 v[238:241], v202, s[16:17] offset:512 nt
	s_waitcnt vmcnt(25)
	v_pk_fma_f32 v[122:123], v[122:123], v[138:139], v[242:243]
	v_pk_fma_f32 v[124:125], v[124:125], v[140:141], v[244:245]
	global_store_dwordx4 v212, v[122:125], s[12:13] sc1 nt
	global_load_dwordx4 v[242:245], v203, s[16:17] nt
	s_waitcnt vmcnt(26)
	v_pk_fma_f32 v[58:59], v[58:59], v[162:163], v[246:247]
	v_pk_fma_f32 v[60:61], v[60:61], v[164:165], v[248:249]
	global_store_dwordx4 v212, v[58:61], s[12:13] offset:512 sc1 nt
	global_load_dwordx4 v[246:249], v203, s[16:17] offset:512 nt
	s_waitcnt vmcnt(26)
	v_pk_fma_f32 v[90:91], v[90:91], v[138:139], v[172:173]
	v_pk_fma_f32 v[92:93], v[92:93], v[140:141], v[174:175]
	global_store_dwordx4 v213, v[90:93], s[12:13] sc1 nt
	global_load_dwordx4 v[172:175], v212, s[16:17] nt
	s_waitcnt vmcnt(26)
	v_pk_fma_f32 v[22:23], v[22:23], v[162:163], v[176:177]
	v_pk_fma_f32 v[24:25], v[24:25], v[164:165], v[178:179]
	global_store_dwordx4 v213, v[22:25], s[12:13] offset:512 sc1 nt
	global_load_dwordx4 v[176:179], v212, s[16:17] offset:512 nt
	s_waitcnt vmcnt(26)
	v_pk_fma_f32 v[118:119], v[118:119], v[138:139], v[186:187]
	v_pk_fma_f32 v[120:121], v[120:121], v[140:141], v[188:189]
	global_store_dwordx4 v166, v[118:121], s[18:19] sc1 nt
	global_load_dwordx4 v[186:189], v213, s[16:17] nt
	s_waitcnt vmcnt(26)
	v_pk_fma_f32 v[50:51], v[50:51], v[162:163], v[190:191]
	v_pk_fma_f32 v[52:53], v[52:53], v[164:165], v[192:193]
	global_store_dwordx4 v166, v[50:53], s[18:19] offset:512 sc1 nt
	global_load_dwordx4 v[190:193], v213, s[16:17] offset:512 nt
	s_waitcnt vmcnt(26)
	v_pk_fma_f32 v[86:87], v[86:87], v[138:139], v[194:195]
	v_pk_fma_f32 v[88:89], v[88:89], v[140:141], v[196:197]
	global_store_dwordx4 v167, v[86:89], s[18:19] sc1 nt
	s_waitcnt vmcnt(25)
	v_pk_fma_f32 v[14:15], v[14:15], v[162:163], v[198:199]
	v_pk_fma_f32 v[16:17], v[16:17], v[164:165], v[200:201]
	global_store_dwordx4 v167, v[14:17], s[18:19] offset:512 sc1 nt
	s_waitcnt vmcnt(24)
	v_pk_fma_f32 v[114:115], v[114:115], v[138:139], v[208:209]
	v_pk_fma_f32 v[116:117], v[116:117], v[140:141], v[210:211]
	global_store_dwordx4 v180, v[114:117], s[18:19] sc1 nt
	s_waitcnt vmcnt(23)
	v_pk_fma_f32 v[42:43], v[42:43], v[162:163], v[218:219]
	v_pk_fma_f32 v[44:45], v[44:45], v[164:165], v[220:221]
	global_store_dwordx4 v180, v[42:45], s[18:19] offset:512 sc1 nt
	s_waitcnt vmcnt(22)
	v_pk_fma_f32 v[78:79], v[78:79], v[138:139], v[226:227]
	v_pk_fma_f32 v[80:81], v[80:81], v[140:141], v[228:229]
	global_store_dwordx4 v181, v[78:81], s[18:19] sc1 nt
	s_waitcnt vmcnt(21)
	v_pk_fma_f32 v[10:11], v[10:11], v[162:163], v[230:231]
	v_pk_fma_f32 v[12:13], v[12:13], v[164:165], v[232:233]
	global_store_dwordx4 v181, v[10:13], s[18:19] offset:512 sc1 nt
	s_waitcnt vmcnt(20)
	v_pk_fma_f32 v[110:111], v[110:111], v[138:139], v[234:235]
	v_pk_fma_f32 v[112:113], v[112:113], v[140:141], v[236:237]
	global_store_dwordx4 v202, v[110:113], s[18:19] sc1 nt
	s_waitcnt vmcnt(19)
	v_pk_fma_f32 v[26:27], v[26:27], v[162:163], v[238:239]
	v_pk_fma_f32 v[28:29], v[28:29], v[164:165], v[240:241]
	global_store_dwordx4 v202, v[26:29], s[18:19] offset:512 sc1 nt
	s_waitcnt vmcnt(18)
	v_pk_fma_f32 v[70:71], v[70:71], v[138:139], v[242:243]
	v_pk_fma_f32 v[72:73], v[72:73], v[140:141], v[244:245]
	global_store_dwordx4 v203, v[70:73], s[18:19] sc1 nt
	s_waitcnt vmcnt(17)
	v_pk_fma_f32 v[6:7], v[6:7], v[162:163], v[246:247]
	v_pk_fma_f32 v[8:9], v[8:9], v[164:165], v[248:249]
	global_store_dwordx4 v203, v[6:9], s[18:19] offset:512 sc1 nt
	s_waitcnt vmcnt(16)
	v_pk_fma_f32 v[94:95], v[94:95], v[138:139], v[172:173]
	v_pk_fma_f32 v[96:97], v[96:97], v[140:141], v[174:175]
	global_store_dwordx4 v212, v[94:97], s[18:19] sc1 nt
	s_waitcnt vmcnt(15)
	v_pk_fma_f32 v[18:19], v[18:19], v[162:163], v[176:177]
	v_pk_fma_f32 v[20:21], v[20:21], v[164:165], v[178:179]
	global_store_dwordx4 v212, v[18:21], s[18:19] offset:512 sc1 nt
	s_waitcnt vmcnt(14)
	v_pk_fma_f32 v[62:63], v[62:63], v[138:139], v[186:187]
	v_pk_fma_f32 v[64:65], v[64:65], v[140:141], v[188:189]
	global_store_dwordx4 v213, v[62:65], s[18:19] sc1 nt
	s_waitcnt vmcnt(13)
	v_pk_fma_f32 v[2:3], v[2:3], v[162:163], v[190:191]
	v_pk_fma_f32 v[4:5], v[4:5], v[164:165], v[192:193]
	global_store_dwordx4 v213, v[2:5], s[18:19] offset:512 sc1 nt
	s_mov_b64 s[10:11], -1
	s_and_b64 vcc, exec, s[4:5]
	s_cbranch_vccnz .LBB0_978
	s_andn2_b64 vcc, exec, s[2:3]
	s_cbranch_vccnz .LBB0_977
	s_barrier
	s_branch .LBB0_977
